# stack11: stack10 + kvc_fix_rows tasks moved to idle workgroups 32..63 (overlaps the prompt kvc pass on workgroups 0..31)
# speedup vs baseline: 1.0064x; 1.0061x over previous
.LBB0_1208:
	s_sub_i32 s10, s10, 0x100
	s_cmp_lt_u32 s10, 0x100
	s_cselect_b64 s[6:7], -1, 0
	s_andn2_b64 vcc, exec, s[6:7]
	s_barrier
	s_cbranch_vccnz .LBB0_1213
	v_lshlrev_b32_e32 v6, 1, v214
	v_mov_b32_e32 v7, 0
	v_lshl_add_u64 v[2:3], s[0:1], 0, v[6:7]
	v_readlane_b32 s0, v248, 0
	v_lshl_add_u64 v[4:5], s[4:5], 0, v[6:7]
	s_bfe_u32 s4, s0, 0x10006
	v_lshlrev_b32_e32 v1, 2, v214
	v_lshl_or_b32 v6, s4, 9, v1
	v_lshl_add_u64 v[8:9], s[80:81], 0, v[6:7]
	s_mov_b64 s[0:1], 0x2a88000
	v_lshl_add_u64 v[10:11], v[8:9], 0, s[0:1]
	s_mov_b32 s0, 0x2a88000
	v_add_co_u32_e32 v8, vcc, s0, v8
	v_lshl_or_b32 v6, s4, 6, v214
	s_nop 0
	v_addc_co_u32_e32 v9, vcc, 0, v9, vcc
	v_readlane_b32 s12, v248, 5
	global_load_dword v1, v[8:9], off
	s_nop 0
	global_load_dword v8, v[10:11], off offset:256
	v_lshlrev_b32_e32 v9, 2, v6
	v_readlane_b32 s26, v248, 19
	v_readlane_b32 s27, v248, 20
	v_mbcnt_lo_u32_b32 v10, -1, 0
	v_mbcnt_hi_u32_b32 v10, -1, v10
	s_mul_i32 s4, s4, 0x11000
	v_lshlrev_b32_e32 v6, 8, v6
	v_lshlrev_b32_e32 v10, 2, v10
	global_load_dword v9, v9, s[26:27]
	s_movk_i32 s0, 0x100
	s_or_b32 s8, s4, 0xff
	v_and_or_b32 v10, v10, s0, 28
	v_lshl_add_u64 v[6:7], s[80:81], 0, v[6:7]
	v_readlane_b32 s13, v248, 6
	v_readlane_b32 s14, v248, 7
	v_readlane_b32 s15, v248, 8
	v_readlane_b32 s16, v248, 9
	v_readlane_b32 s17, v248, 10
	v_readlane_b32 s18, v248, 11
	v_readlane_b32 s19, v248, 12
	v_readlane_b32 s20, v248, 13
	v_readlane_b32 s21, v248, 14
	v_readlane_b32 s22, v248, 15
	v_readlane_b32 s23, v248, 16
	v_readlane_b32 s24, v248, 17
	v_readlane_b32 s25, v248, 18
